# speedup vs baseline: 1.0027x; 1.0027x over previous
; __device__ __forceinline__ void gemm_phase(const Params& P, const GArgs& ga, int wid_s, int first, int stride) {
;   const int nN = ga.N / BM;
;   const int nM = ga.split ? NP / BM : NTOK / BM;
;   const int nwg = nM * nN;
;   const int nitems = ga.split ? nwg + (NS / BM) * nN * 8 : nwg;
;   const int nkt_all = ga.K / BK;
;   for (int t = first; t < nitems; t += stride) {
.LBB0_288:
	s_and_b64 s[8:9], s[4:5], exec
	s_cselect_b32 s41, 0x44, 64
	s_mul_i32 s54, s78, s41
	s_lshl_b32 s8, s78, 5
	s_add_i32 s8, s54, s8
	s_and_b64 s[4:5], s[4:5], exec
	s_cselect_b32 s91, s54, s8
	s_cmp_ge_i32 s59, s91
	s_cbranch_scc1 .LBB0_261
	v_cvt_f32_u32_e32 v0, s78
	s_lshl_b32 s44, s78, 2
	v_cvt_f32_u32_e32 v2, s44
	s_xor_b64 s[34:35], s[0:1], -1
	v_rcp_iflag_f32_e32 v0, v0
	s_sub_i32 s0, 0, s78
	v_rcp_iflag_f32_e32 v2, v2
	s_mov_b64 s[36:37], s[84:85]
	v_mul_f32_e32 v0, 0x4f7ffffe, v0
	v_cvt_u32_f32_e32 v0, v0
	s_xor_b64 s[96:97], s[6:7], -1
	s_lshr_b32 s76, s93, 6
	s_lshr_b32 s42, s93, 9
	v_readfirstlane_b32 s1, v0
	v_mul_f32_e32 v0, 0x4f7ffffe, v2
	v_cvt_u32_f32_e32 v0, v0
	s_mul_i32 s0, s0, s1
	s_mul_hi_u32 s0, s1, s0
	s_add_i32 s45, s1, s0
	s_sub_i32 s0, 0, s44
	v_readfirstlane_b32 s1, v0
	s_mul_i32 s0, s0, s1
	s_mul_hi_u32 s0, s1, s0
	s_lshr_b32 s43, s54, 3
	s_mov_b32 s21, s20
	s_add_i32 s46, s1, s0
	s_lshl_b32 s47, s93, 7
	s_lshl_b32 s48, s93, 1
	s_lshl_b32 s49, s93, 9
	s_bitcmp1_b32 s59, 3
	s_cbranch_scc0 .Ldsy_skip
	s_memrealtime s[0:1]
	s_waitcnt lgkmcnt(0)
	s_add_u32 s0, s0, 300
	s_addc_u32 s1, s1, 0
